# hand-written mode-1 DeepNorm residual epilogue: all Z/stats/gate/LN loads hoisted up front, LDS transposes pipelined
# speedup vs baseline: 1.0302x; 1.0302x over previous
; #define PG8_LAS __attribute__((address_space(3)))
; #define PG8_GAS __attribute__((address_space(1)))
;     __device__ __forceinline__ void operator()(const f32x4 (&acc)[2][2][4][2], const Unit& u, int wr, int wc, int fr, int fq) const {
;         const int b = u.pm >> 5, lane = fr + 16 * fq;
;         PG8_LAS unsigned char* sw = (PG8_LAS unsigned char*)(size_t)(scr + (unsigned)(wr * 4 + wc) * 2048u);
;         const int wrow = fr * 128, rrow = lane >> 3, rch = lane & 7;
;         f32x4 gt[2], lg[2], lb[2];
; #pragma unroll
;         for (int bj = 0; bj < 2; ++bj) {
;             const int c = u.pn * BM + bj * HALF + wc * 32 + 4 * rch;
;             gt[bj] = (*(const PG8_GAS f32x4*)(gate + (size_t)b * 9216 + c) + 1.f) * resw;
;             lg[bj] = (f32x4){1.f, 1.f, 1.f, 1.f}; lb[bj] = (f32x4){0.f, 0.f, 0.f, 0.f};
;             if (mode) { lg[bj] = *(const PG8_GAS f32x4*)(lng + c); lb[bj] = *(const PG8_GAS f32x4*)(lnb + c); }
;         }
; #pragma unroll
;         for (int ai = 0; ai < 2; ++ai)
; #pragma unroll
;             for (int m = 0; m < 4; ++m) {
;                 const int r0 = u.pm * BM + ai * HALF + wr * 64 + m * 16;
;                 f32x2 st2[2];
; #pragma unroll
;                 for (int s = 0; s < 2; ++s) { st2[s] = (f32x2){0.f, 1.f}; if (mode) st2[s] = *(const PG8_GAS f32x2*)(stats + 2 * (size_t)(r0 + 8 * s + rrow)); }
; #pragma unroll
;                 for (int bj = 0; bj < 2; ++bj) {
;                     const size_t off0 = (size_t)(r0 + rrow) * 1024 + u.pn * BM + bj * HALF + wc * 32 + 4 * rch;
;                     f32x4 xo[2];
; #pragma unroll
;                     for (int s = 0; s < 2; ++s) {
;                         if (!mode) xo[s] = *(const PG8_GAS f32x4*)(xin + off0 + (size_t)s * 8192);
;                         else { const u32x2 w = *(const PG8_GAS u32x2*)(Z + off0 + (size_t)s * 8192);
;                             xo[s] = (f32x4){__builtin_bit_cast(float, w.x << 16), __builtin_bit_cast(float, w.x & 0xffff0000u), __builtin_bit_cast(float, w.y << 16), __builtin_bit_cast(float, w.y & 0xffff0000u)}; }
;                     }
; #pragma unroll
;                     for (int n = 0; n < 2; ++n) *(PG8_LAS f32x4*)(sw + wrow + (((4 * n + fq) ^ (fr & 7)) << 4)) = acc[ai][bj][m][n];
;                     asm volatile("s_waitcnt lgkmcnt(0)" ::: "memory");
;                     f32x4 av[2];
; #pragma unroll
.LBB0_1308:
	s_and_b64 vcc, exec, s[2:3]
	s_cbranch_vccz .Lres_m0
	s_ashr_i32 s8, s67, 5
	s_mul_hi_i32 s9, s8, 0x9000
	s_mul_i32 s8, s8, 0x9000
	s_add_u32 s8, s51, s8
	s_addc_u32 s9, s56, s9
	s_lshl_b32 s32, s72, 10
	s_add_u32 s8, s8, s32
	s_addc_u32 s9, s9, 0
	v_lshlrev_b32_e32 v212, 2, v180
	s_add_u32 s54, s14, s32
	s_addc_u32 s55, s15, 0
	s_add_u32 s98, s16, s32
	s_addc_u32 s99, s17, 0
	global_load_dwordx4 v[32:35], v212, s[8:9]
	global_load_dwordx4 v[36:39], v212, s[8:9] offset:512
	global_load_dwordx4 v[48:51], v212, s[54:55]
	global_load_dwordx4 v[52:55], v212, s[54:55] offset:512
	global_load_dwordx4 v[144:147], v212, s[98:99]
	global_load_dwordx4 v[148:151], v212, s[98:99] offset:512
	s_lshl_b32 s8, s67, 8
	s_add_i32 s8, s8, s61
	s_lshl_b32 s9, s8, 3
	s_add_u32 s28, s74, s9
	s_addc_u32 s29, s75, 0
	v_lshlrev_b32_e32 v209, 3, v202
	global_load_dwordx2 v[152:153], v209, s[28:29]
	global_load_dwordx2 v[154:155], v209, s[28:29] offset:64
	global_load_dwordx2 v[156:157], v209, s[28:29] offset:128
	global_load_dwordx2 v[158:159], v209, s[28:29] offset:192
	global_load_dwordx2 v[166:167], v209, s[28:29] offset:256
	global_load_dwordx2 v[168:169], v209, s[28:29] offset:320
	global_load_dwordx2 v[188:189], v209, s[28:29] offset:384
	global_load_dwordx2 v[190:191], v209, s[28:29] offset:448
	s_lshl_b32 s9, s8, 11
	s_lshl_b32 s32, s72, 9
	s_add_u32 s9, s9, s32
	s_add_u32 s24, s12, s9
	s_addc_u32 s25, s13, 0
	s_add_u32 s26, s24, 0x4000
	s_addc_u32 s27, s25, 0
	s_mov_b64 s[30:31], s[24:25]
	s_mov_b64 s[100:101], s[26:27]
	v_lshlrev_b32_e32 v203, 11, v202
	v_lshl_add_u32 v203, v180, 1, v203
	global_load_dwordx2 v[200:201], v203, s[24:25]
	global_load_dwordx2 v[222:223], v203, s[26:27]
	global_load_dwordx2 v[224:225], v203, s[24:25] offset:256
	global_load_dwordx2 v[226:227], v203, s[26:27] offset:256
	s_add_u32 s24, s24, 0x8000
	s_addc_u32 s25, s25, 0
	s_add_u32 s26, s26, 0x8000
	s_addc_u32 s27, s27, 0
	global_load_dwordx2 v[228:229], v203, s[24:25]
	global_load_dwordx2 v[230:231], v203, s[26:27]
	global_load_dwordx2 v[232:233], v203, s[24:25] offset:256
	global_load_dwordx2 v[234:235], v203, s[26:27] offset:256
	s_add_u32 s24, s24, 0x8000
	s_addc_u32 s25, s25, 0
	s_add_u32 s26, s26, 0x8000
	s_addc_u32 s27, s27, 0
	global_load_dwordx2 v[236:237], v203, s[24:25]
	global_load_dwordx2 v[238:239], v203, s[26:27]
	global_load_dwordx2 v[240:241], v203, s[24:25] offset:256
	global_load_dwordx2 v[242:243], v203, s[26:27] offset:256
	s_add_u32 s24, s24, 0x8000
	s_addc_u32 s25, s25, 0
	s_add_u32 s26, s26, 0x8000
	s_addc_u32 s27, s27, 0
	global_load_dwordx2 v[244:245], v203, s[24:25]
	global_load_dwordx2 v[246:247], v203, s[26:27]
	global_load_dwordx2 v[248:249], v203, s[24:25] offset:256
	global_load_dwordx2 v[250:251], v203, s[26:27] offset:256
	s_add_u32 s24, s24, 0x28000
	s_addc_u32 s25, s25, 0
	s_add_u32 s26, s26, 0x28000
	s_addc_u32 s27, s27, 0
	ds_write_b128 v219, v[140:143]
	ds_write_b128 v220, v[136:139]
	s_waitcnt lgkmcnt(0)
	ds_read_b128 v[140:143], v221
	ds_read_b128 v[136:139], v221 offset:1024
	s_waitcnt vmcnt(14)
	v_add_f32_e32 v32, 1.0, v32
	v_add_f32_e32 v33, 1.0, v33
	v_add_f32_e32 v34, 1.0, v34
	v_add_f32_e32 v35, 1.0, v35
	v_add_f32_e32 v36, 1.0, v36
	v_add_f32_e32 v37, 1.0, v37
	v_add_f32_e32 v38, 1.0, v38
	v_add_f32_e32 v39, 1.0, v39
	v_mul_f32_e32 v32, v162, v32
	v_mul_f32_e32 v33, v162, v33
	v_mul_f32_e32 v34, v162, v34
	v_mul_f32_e32 v35, v162, v35
	v_mul_f32_e32 v36, v162, v36
	v_mul_f32_e32 v37, v162, v37
	v_mul_f32_e32 v38, v162, v38
	v_mul_f32_e32 v39, v162, v39
	v_lshlrev_b32_e32 v192, 16, v200
	v_and_b32_e32 v193, 0xffff0000, v200
	v_lshlrev_b32_e32 v194, 16, v201
	v_and_b32_e32 v195, 0xffff0000, v201
	v_sub_f32_e32 v192, v192, v152
	v_sub_f32_e32 v193, v193, v152
	v_sub_f32_e32 v194, v194, v152
	v_sub_f32_e32 v195, v195, v152
	v_pk_mul_f32 v[192:193], v[152:153], v[192:193] op_sel:[1,0]
	v_pk_mul_f32 v[194:195], v[152:153], v[194:195] op_sel:[1,0]
	v_pk_fma_f32 v[192:193], v[48:49], v[192:193], v[144:145]
	v_pk_fma_f32 v[194:195], v[50:51], v[194:195], v[146:147]
	v_pk_mul_f32 v[192:193], v[192:193], s[46:47] op_sel_hi:[1,0]
	v_pk_mul_f32 v[194:195], v[194:195], s[46:47] op_sel_hi:[1,0]
	v_lshlrev_b32_e32 v196, 16, v222
	v_and_b32_e32 v197, 0xffff0000, v222
	v_lshlrev_b32_e32 v198, 16, v223
	v_and_b32_e32 v199, 0xffff0000, v223
	v_sub_f32_e32 v196, v196, v154
	v_sub_f32_e32 v197, v197, v154
	v_sub_f32_e32 v198, v198, v154
	v_sub_f32_e32 v199, v199, v154
	v_pk_mul_f32 v[196:197], v[154:155], v[196:197] op_sel:[1,0]
	v_pk_mul_f32 v[198:199], v[154:155], v[198:199] op_sel:[1,0]
	v_pk_fma_f32 v[196:197], v[48:49], v[196:197], v[144:145]
	v_pk_fma_f32 v[198:199], v[50:51], v[198:199], v[146:147]
	v_pk_mul_f32 v[196:197], v[196:197], s[46:47] op_sel_hi:[1,0]
	v_pk_mul_f32 v[198:199], v[198:199], s[46:47] op_sel_hi:[1,0]
	s_waitcnt lgkmcnt(0)
	ds_write_b128 v219, v[132:135]
	ds_write_b128 v220, v[128:131]
	v_pk_fma_f32 v[192:193], v[32:33], v[140:141], v[192:193]
	v_pk_fma_f32 v[194:195], v[34:35], v[142:143], v[194:195]
	v_cvt_pk_bf16_f32 v192, v192, v193
	v_cvt_pk_bf16_f32 v193, v194, v195
	global_store_dwordx2 v203, v[192:193], s[30:31]
	v_pk_fma_f32 v[196:197], v[32:33], v[136:137], v[196:197]
	v_pk_fma_f32 v[198:199], v[34:35], v[138:139], v[198:199]
	v_cvt_pk_bf16_f32 v196, v196, v197
	v_cvt_pk_bf16_f32 v197, v198, v199
	global_store_dwordx2 v203, v[196:197], s[100:101]
	global_load_dwordx2 v[136:137], v209, s[28:29] offset:1024
	global_load_dwordx2 v[138:139], v209, s[28:29] offset:1088
	global_load_dwordx2 v[140:141], v209, s[28:29] offset:1152
	global_load_dwordx2 v[142:143], v209, s[28:29] offset:1216
	s_waitcnt lgkmcnt(0)
; #define PG8_LAS __attribute__((address_space(3)))
; __device__ __forceinline__ unsigned cvt_pk_bf16(float lo, float hi) { const f32x2c v = {lo, hi}; const bf16x2c b = __builtin_convertvector(v, bf16x2c); return __builtin_bit_cast(unsigned, b); }
;     __device__ __forceinline__ void operator()(const f32x4 (&acc)[2][2][4][2], const Unit& u, int wr, int wc, int fr, int fq) const {
;     ...
;                 const int r0 = u.pm * BM + ai * HALF + wr * 64 + m * 16;
;                 f32x2 st2[2];
; #pragma unroll
;                 for (int s = 0; s < 2; ++s) { st2[s] = (f32x2){0.f, 1.f}; if (mode) st2[s] = *(const PG8_GAS f32x2*)(stats + 2 * (size_t)(r0 + 8 * s + rrow)); }
; #pragma unroll
;                 for (int bj = 0; bj < 2; ++bj) {
;                     const size_t off0 = (size_t)(r0 + rrow) * 1024 + u.pn * BM + bj * HALF + wc * 32 + 4 * rch;
;                     f32x4 xo[2];
; #pragma unroll
;                     for (int s = 0; s < 2; ++s) {
;                         if (!mode) xo[s] = *(const PG8_GAS f32x4*)(xin + off0 + (size_t)s * 8192);
;                         else { const u32x2 w = *(const PG8_GAS u32x2*)(Z + off0 + (size_t)s * 8192);
;                             xo[s] = (f32x4){__builtin_bit_cast(float, w.x << 16), __builtin_bit_cast(float, w.x & 0xffff0000u), __builtin_bit_cast(float, w.y << 16), __builtin_bit_cast(float, w.y & 0xffff0000u)}; }
;                     }
; #pragma unroll
;                     for (int n = 0; n < 2; ++n) *(PG8_LAS f32x4*)(sw + wrow + (((4 * n + fq) ^ (fr & 7)) << 4)) = acc[ai][bj][m][n];
;                     asm volatile("s_waitcnt lgkmcnt(0)" ::: "memory");
;                     f32x4 av[2];
; #pragma unroll
;                     for (int s = 0; s < 2; ++s) av[s] = *(const PG8_LAS f32x4*)(sw + (8 * s + rrow) * 128 + ((rch ^ ((8 * s + rrow) & 7)) << 4));
;                     asm volatile("s_waitcnt lgkmcnt(0)" ::: "memory");
; #pragma unroll
;                     for (int s = 0; s < 2; ++s) {
;                         f32x4 xv = xo[s];
;                         if (mode) xv = (xv - st2[s].x) * st2[s].y * lg[bj] + lb[bj];
;                         const f32x4 zz = xv * alpha + gt[bj] * av[s];
;                         u32x2 zp; zp.x = cvt_pk_bf16(zz.x, zz.y); zp.y = cvt_pk_bf16(zz.z, zz.w);
;                         *(PG8_GAS u32x2*)(Z + off0 + (size_t)s * 8192) = zp;
;                     }
	ds_read_b128 v[132:135], v221
	ds_read_b128 v[128:131], v221 offset:1024
	s_waitcnt vmcnt(18)
	v_lshlrev_b32_e32 v192, 16, v224
	v_and_b32_e32 v193, 0xffff0000, v224
	v_lshlrev_b32_e32 v194, 16, v225
	v_and_b32_e32 v195, 0xffff0000, v225
	v_sub_f32_e32 v192, v192, v152
	v_sub_f32_e32 v193, v193, v152
	v_sub_f32_e32 v194, v194, v152
	v_sub_f32_e32 v195, v195, v152
	v_pk_mul_f32 v[192:193], v[152:153], v[192:193] op_sel:[1,0]
	v_pk_mul_f32 v[194:195], v[152:153], v[194:195] op_sel:[1,0]
	v_pk_fma_f32 v[192:193], v[52:53], v[192:193], v[148:149]
	v_pk_fma_f32 v[194:195], v[54:55], v[194:195], v[150:151]
	v_pk_mul_f32 v[192:193], v[192:193], s[46:47] op_sel_hi:[1,0]
	v_pk_mul_f32 v[194:195], v[194:195], s[46:47] op_sel_hi:[1,0]
	v_lshlrev_b32_e32 v196, 16, v226
	v_and_b32_e32 v197, 0xffff0000, v226
	v_lshlrev_b32_e32 v198, 16, v227
	v_and_b32_e32 v199, 0xffff0000, v227
	v_sub_f32_e32 v196, v196, v154
	v_sub_f32_e32 v197, v197, v154
	v_sub_f32_e32 v198, v198, v154
	v_sub_f32_e32 v199, v199, v154
	v_pk_mul_f32 v[196:197], v[154:155], v[196:197] op_sel:[1,0]
	v_pk_mul_f32 v[198:199], v[154:155], v[198:199] op_sel:[1,0]
	v_pk_fma_f32 v[196:197], v[52:53], v[196:197], v[148:149]
	v_pk_fma_f32 v[198:199], v[54:55], v[198:199], v[150:151]
	v_pk_mul_f32 v[196:197], v[196:197], s[46:47] op_sel_hi:[1,0]
	v_pk_mul_f32 v[198:199], v[198:199], s[46:47] op_sel_hi:[1,0]
	s_waitcnt lgkmcnt(0)
	ds_write_b128 v219, v[124:127]
	ds_write_b128 v220, v[120:123]
	v_pk_fma_f32 v[192:193], v[36:37], v[132:133], v[192:193]
	v_pk_fma_f32 v[194:195], v[38:39], v[134:135], v[194:195]
	v_cvt_pk_bf16_f32 v192, v192, v193
	v_cvt_pk_bf16_f32 v193, v194, v195
	global_store_dwordx2 v203, v[192:193], s[30:31] offset:256
	v_pk_fma_f32 v[196:197], v[36:37], v[128:129], v[196:197]
	v_pk_fma_f32 v[198:199], v[38:39], v[130:131], v[198:199]
	v_cvt_pk_bf16_f32 v196, v196, v197
	v_cvt_pk_bf16_f32 v197, v198, v199
	global_store_dwordx2 v203, v[196:197], s[100:101] offset:256
	s_add_u32 s30, s30, 0x8000
	s_addc_u32 s31, s31, 0
	s_add_u32 s100, s100, 0x8000
	s_addc_u32 s101, s101, 0
	global_load_dwordx2 v[128:129], v209, s[28:29] offset:1280
	global_load_dwordx2 v[130:131], v209, s[28:29] offset:1344
	global_load_dwordx2 v[132:133], v209, s[28:29] offset:1408
	global_load_dwordx2 v[134:135], v209, s[28:29] offset:1472
	s_waitcnt lgkmcnt(0)
	ds_read_b128 v[124:127], v221
	ds_read_b128 v[120:123], v221 offset:1024
	s_waitcnt vmcnt(22)
	v_lshlrev_b32_e32 v192, 16, v228
	v_and_b32_e32 v193, 0xffff0000, v228
	v_lshlrev_b32_e32 v194, 16, v229
	v_and_b32_e32 v195, 0xffff0000, v229
	v_sub_f32_e32 v192, v192, v156
	v_sub_f32_e32 v193, v193, v156
	v_sub_f32_e32 v194, v194, v156
	v_sub_f32_e32 v195, v195, v156
	v_pk_mul_f32 v[192:193], v[156:157], v[192:193] op_sel:[1,0]
	v_pk_mul_f32 v[194:195], v[156:157], v[194:195] op_sel:[1,0]
	v_pk_fma_f32 v[192:193], v[48:49], v[192:193], v[144:145]
	v_pk_fma_f32 v[194:195], v[50:51], v[194:195], v[146:147]
	v_pk_mul_f32 v[192:193], v[192:193], s[46:47] op_sel_hi:[1,0]
	v_pk_mul_f32 v[194:195], v[194:195], s[46:47] op_sel_hi:[1,0]
	v_lshlrev_b32_e32 v196, 16, v230
	v_and_b32_e32 v197, 0xffff0000, v230
	v_lshlrev_b32_e32 v198, 16, v231
	v_and_b32_e32 v199, 0xffff0000, v231
	v_sub_f32_e32 v196, v196, v158
	v_sub_f32_e32 v197, v197, v158
	v_sub_f32_e32 v198, v198, v158
	v_sub_f32_e32 v199, v199, v158
	v_pk_mul_f32 v[196:197], v[158:159], v[196:197] op_sel:[1,0]
	v_pk_mul_f32 v[198:199], v[158:159], v[198:199] op_sel:[1,0]
	v_pk_fma_f32 v[196:197], v[48:49], v[196:197], v[144:145]
	v_pk_fma_f32 v[198:199], v[50:51], v[198:199], v[146:147]
	v_pk_mul_f32 v[196:197], v[196:197], s[46:47] op_sel_hi:[1,0]
	v_pk_mul_f32 v[198:199], v[198:199], s[46:47] op_sel_hi:[1,0]
	s_waitcnt lgkmcnt(0)
	ds_write_b128 v219, v[116:119]
	ds_write_b128 v220, v[112:115]
	v_pk_fma_f32 v[192:193], v[32:33], v[124:125], v[192:193]
	v_pk_fma_f32 v[194:195], v[34:35], v[126:127], v[194:195]
	v_cvt_pk_bf16_f32 v192, v192, v193
	v_cvt_pk_bf16_f32 v193, v194, v195
	global_store_dwordx2 v203, v[192:193], s[30:31]
	v_pk_fma_f32 v[196:197], v[32:33], v[120:121], v[196:197]
	v_pk_fma_f32 v[198:199], v[34:35], v[122:123], v[198:199]
	v_cvt_pk_bf16_f32 v196, v196, v197
	v_cvt_pk_bf16_f32 v197, v198, v199
	global_store_dwordx2 v203, v[196:197], s[100:101]
	global_load_dwordx2 v[120:121], v203, s[24:25]
	global_load_dwordx2 v[122:123], v203, s[26:27]
	global_load_dwordx2 v[124:125], v203, s[24:25] offset:256
	global_load_dwordx2 v[126:127], v203, s[26:27] offset:256
	s_add_u32 s24, s24, 0x8000
	s_addc_u32 s25, s25, 0
	s_add_u32 s26, s26, 0x8000
	s_addc_u32 s27, s27, 0
	s_waitcnt lgkmcnt(0)
	ds_read_b128 v[116:119], v221
	ds_read_b128 v[112:115], v221 offset:1024
	s_waitcnt vmcnt(26)
	v_lshlrev_b32_e32 v192, 16, v232
	v_and_b32_e32 v193, 0xffff0000, v232
	v_lshlrev_b32_e32 v194, 16, v233
	v_and_b32_e32 v195, 0xffff0000, v233
	v_sub_f32_e32 v192, v192, v156
	v_sub_f32_e32 v193, v193, v156
	v_sub_f32_e32 v194, v194, v156
	v_sub_f32_e32 v195, v195, v156
	v_pk_mul_f32 v[192:193], v[156:157], v[192:193] op_sel:[1,0]
	v_pk_mul_f32 v[194:195], v[156:157], v[194:195] op_sel:[1,0]
	v_pk_fma_f32 v[192:193], v[52:53], v[192:193], v[148:149]
	v_pk_fma_f32 v[194:195], v[54:55], v[194:195], v[150:151]
	v_pk_mul_f32 v[192:193], v[192:193], s[46:47] op_sel_hi:[1,0]
	v_pk_mul_f32 v[194:195], v[194:195], s[46:47] op_sel_hi:[1,0]
	v_lshlrev_b32_e32 v196, 16, v234
	v_and_b32_e32 v197, 0xffff0000, v234
	v_lshlrev_b32_e32 v198, 16, v235
	v_and_b32_e32 v199, 0xffff0000, v235
	v_sub_f32_e32 v196, v196, v158
	v_sub_f32_e32 v197, v197, v158
	v_sub_f32_e32 v198, v198, v158
	v_sub_f32_e32 v199, v199, v158
	v_pk_mul_f32 v[196:197], v[158:159], v[196:197] op_sel:[1,0]
	v_pk_mul_f32 v[198:199], v[158:159], v[198:199] op_sel:[1,0]
	v_pk_fma_f32 v[196:197], v[52:53], v[196:197], v[148:149]
	v_pk_fma_f32 v[198:199], v[54:55], v[198:199], v[150:151]
	v_pk_mul_f32 v[196:197], v[196:197], s[46:47] op_sel_hi:[1,0]
	v_pk_mul_f32 v[198:199], v[198:199], s[46:47] op_sel_hi:[1,0]
	s_waitcnt lgkmcnt(0)
; #define PG8_LAS __attribute__((address_space(3)))
; __device__ __forceinline__ unsigned cvt_pk_bf16(float lo, float hi) { const f32x2c v = {lo, hi}; const bf16x2c b = __builtin_convertvector(v, bf16x2c); return __builtin_bit_cast(unsigned, b); }
;     __device__ __forceinline__ void operator()(const f32x4 (&acc)[2][2][4][2], const Unit& u, int wr, int wc, int fr, int fq) const {
;     ...
;                 const int r0 = u.pm * BM + ai * HALF + wr * 64 + m * 16;
;                 f32x2 st2[2];
; #pragma unroll
;                 for (int s = 0; s < 2; ++s) { st2[s] = (f32x2){0.f, 1.f}; if (mode) st2[s] = *(const PG8_GAS f32x2*)(stats + 2 * (size_t)(r0 + 8 * s + rrow)); }
; #pragma unroll
;                 for (int bj = 0; bj < 2; ++bj) {
;                     const size_t off0 = (size_t)(r0 + rrow) * 1024 + u.pn * BM + bj * HALF + wc * 32 + 4 * rch;
;                     f32x4 xo[2];
; #pragma unroll
;                     for (int s = 0; s < 2; ++s) {
;                         if (!mode) xo[s] = *(const PG8_GAS f32x4*)(xin + off0 + (size_t)s * 8192);
;                         else { const u32x2 w = *(const PG8_GAS u32x2*)(Z + off0 + (size_t)s * 8192);
;                             xo[s] = (f32x4){__builtin_bit_cast(float, w.x << 16), __builtin_bit_cast(float, w.x & 0xffff0000u), __builtin_bit_cast(float, w.y << 16), __builtin_bit_cast(float, w.y & 0xffff0000u)}; }
;                     }
; #pragma unroll
;                     for (int n = 0; n < 2; ++n) *(PG8_LAS f32x4*)(sw + wrow + (((4 * n + fq) ^ (fr & 7)) << 4)) = acc[ai][bj][m][n];
;                     asm volatile("s_waitcnt lgkmcnt(0)" ::: "memory");
;                     f32x4 av[2];
; #pragma unroll
;                     for (int s = 0; s < 2; ++s) av[s] = *(const PG8_LAS f32x4*)(sw + (8 * s + rrow) * 128 + ((rch ^ ((8 * s + rrow) & 7)) << 4));
;                     asm volatile("s_waitcnt lgkmcnt(0)" ::: "memory");
; #pragma unroll
;                     for (int s = 0; s < 2; ++s) {
;                         f32x4 xv = xo[s];
;                         if (mode) xv = (xv - st2[s].x) * st2[s].y * lg[bj] + lb[bj];
;                         const f32x4 zz = xv * alpha + gt[bj] * av[s];
;                         u32x2 zp; zp.x = cvt_pk_bf16(zz.x, zz.y); zp.y = cvt_pk_bf16(zz.z, zz.w);
;                         *(PG8_GAS u32x2*)(Z + off0 + (size_t)s * 8192) = zp;
;                     }
	ds_write_b128 v219, v[108:111]
	ds_write_b128 v220, v[104:107]
	v_pk_fma_f32 v[192:193], v[36:37], v[116:117], v[192:193]
	v_pk_fma_f32 v[194:195], v[38:39], v[118:119], v[194:195]
	v_cvt_pk_bf16_f32 v192, v192, v193
	v_cvt_pk_bf16_f32 v193, v194, v195
	global_store_dwordx2 v203, v[192:193], s[30:31] offset:256
	v_pk_fma_f32 v[196:197], v[36:37], v[112:113], v[196:197]
	v_pk_fma_f32 v[198:199], v[38:39], v[114:115], v[198:199]
	v_cvt_pk_bf16_f32 v196, v196, v197
	v_cvt_pk_bf16_f32 v197, v198, v199
	global_store_dwordx2 v203, v[196:197], s[100:101] offset:256
	s_add_u32 s30, s30, 0x8000
	s_addc_u32 s31, s31, 0
	s_add_u32 s100, s100, 0x8000
	s_addc_u32 s101, s101, 0
	global_load_dwordx2 v[112:113], v203, s[24:25]
	global_load_dwordx2 v[114:115], v203, s[26:27]
	global_load_dwordx2 v[116:117], v203, s[24:25] offset:256
	global_load_dwordx2 v[118:119], v203, s[26:27] offset:256
	s_add_u32 s24, s24, 0x8000
	s_addc_u32 s25, s25, 0
	s_add_u32 s26, s26, 0x8000
	s_addc_u32 s27, s27, 0
	s_waitcnt lgkmcnt(0)
	ds_read_b128 v[108:111], v221
	ds_read_b128 v[104:107], v221 offset:1024
	s_waitcnt vmcnt(30)
	v_lshlrev_b32_e32 v192, 16, v236
	v_and_b32_e32 v193, 0xffff0000, v236
	v_lshlrev_b32_e32 v194, 16, v237
	v_and_b32_e32 v195, 0xffff0000, v237
	v_sub_f32_e32 v192, v192, v166
	v_sub_f32_e32 v193, v193, v166
	v_sub_f32_e32 v194, v194, v166
	v_sub_f32_e32 v195, v195, v166
	v_pk_mul_f32 v[192:193], v[166:167], v[192:193] op_sel:[1,0]
	v_pk_mul_f32 v[194:195], v[166:167], v[194:195] op_sel:[1,0]
	v_pk_fma_f32 v[192:193], v[48:49], v[192:193], v[144:145]
	v_pk_fma_f32 v[194:195], v[50:51], v[194:195], v[146:147]
	v_pk_mul_f32 v[192:193], v[192:193], s[46:47] op_sel_hi:[1,0]
	v_pk_mul_f32 v[194:195], v[194:195], s[46:47] op_sel_hi:[1,0]
	v_lshlrev_b32_e32 v196, 16, v238
	v_and_b32_e32 v197, 0xffff0000, v238
	v_lshlrev_b32_e32 v198, 16, v239
	v_and_b32_e32 v199, 0xffff0000, v239
	v_sub_f32_e32 v196, v196, v168
	v_sub_f32_e32 v197, v197, v168
	v_sub_f32_e32 v198, v198, v168
	v_sub_f32_e32 v199, v199, v168
	v_pk_mul_f32 v[196:197], v[168:169], v[196:197] op_sel:[1,0]
	v_pk_mul_f32 v[198:199], v[168:169], v[198:199] op_sel:[1,0]
	v_pk_fma_f32 v[196:197], v[48:49], v[196:197], v[144:145]
	v_pk_fma_f32 v[198:199], v[50:51], v[198:199], v[146:147]
	v_pk_mul_f32 v[196:197], v[196:197], s[46:47] op_sel_hi:[1,0]
	v_pk_mul_f32 v[198:199], v[198:199], s[46:47] op_sel_hi:[1,0]
	s_waitcnt lgkmcnt(0)
	ds_write_b128 v219, v[100:103]
	ds_write_b128 v220, v[96:99]
	v_pk_fma_f32 v[192:193], v[32:33], v[108:109], v[192:193]
	v_pk_fma_f32 v[194:195], v[34:35], v[110:111], v[194:195]
	v_cvt_pk_bf16_f32 v192, v192, v193
	v_cvt_pk_bf16_f32 v193, v194, v195
	global_store_dwordx2 v203, v[192:193], s[30:31]
	v_pk_fma_f32 v[196:197], v[32:33], v[104:105], v[196:197]
	v_pk_fma_f32 v[198:199], v[34:35], v[106:107], v[198:199]
	v_cvt_pk_bf16_f32 v196, v196, v197
	v_cvt_pk_bf16_f32 v197, v198, v199
	global_store_dwordx2 v203, v[196:197], s[100:101]
	global_load_dwordx2 v[104:105], v203, s[24:25]
	global_load_dwordx2 v[106:107], v203, s[26:27]
	global_load_dwordx2 v[108:109], v203, s[24:25] offset:256
	global_load_dwordx2 v[110:111], v203, s[26:27] offset:256
	s_add_u32 s24, s24, 0x8000
	s_addc_u32 s25, s25, 0
	s_add_u32 s26, s26, 0x8000
	s_addc_u32 s27, s27, 0
	s_waitcnt lgkmcnt(0)
	ds_read_b128 v[100:103], v221
	ds_read_b128 v[96:99], v221 offset:1024
	s_waitcnt vmcnt(34)
	v_lshlrev_b32_e32 v192, 16, v240
	v_and_b32_e32 v193, 0xffff0000, v240
	v_lshlrev_b32_e32 v194, 16, v241
	v_and_b32_e32 v195, 0xffff0000, v241
	v_sub_f32_e32 v192, v192, v166
	v_sub_f32_e32 v193, v193, v166
	v_sub_f32_e32 v194, v194, v166
	v_sub_f32_e32 v195, v195, v166
	v_pk_mul_f32 v[192:193], v[166:167], v[192:193] op_sel:[1,0]
	v_pk_mul_f32 v[194:195], v[166:167], v[194:195] op_sel:[1,0]
	v_pk_fma_f32 v[192:193], v[52:53], v[192:193], v[148:149]
	v_pk_fma_f32 v[194:195], v[54:55], v[194:195], v[150:151]
	v_pk_mul_f32 v[192:193], v[192:193], s[46:47] op_sel_hi:[1,0]
	v_pk_mul_f32 v[194:195], v[194:195], s[46:47] op_sel_hi:[1,0]
	v_lshlrev_b32_e32 v196, 16, v242
	v_and_b32_e32 v197, 0xffff0000, v242
	v_lshlrev_b32_e32 v198, 16, v243
	v_and_b32_e32 v199, 0xffff0000, v243
	v_sub_f32_e32 v196, v196, v168
	v_sub_f32_e32 v197, v197, v168
	v_sub_f32_e32 v198, v198, v168
	v_sub_f32_e32 v199, v199, v168
	v_pk_mul_f32 v[196:197], v[168:169], v[196:197] op_sel:[1,0]
	v_pk_mul_f32 v[198:199], v[168:169], v[198:199] op_sel:[1,0]
	v_pk_fma_f32 v[196:197], v[52:53], v[196:197], v[148:149]
	v_pk_fma_f32 v[198:199], v[54:55], v[198:199], v[150:151]
	v_pk_mul_f32 v[196:197], v[196:197], s[46:47] op_sel_hi:[1,0]
	v_pk_mul_f32 v[198:199], v[198:199], s[46:47] op_sel_hi:[1,0]
	s_waitcnt lgkmcnt(0)
	ds_write_b128 v219, v[92:95]
	ds_write_b128 v220, v[88:91]
	v_pk_fma_f32 v[192:193], v[36:37], v[100:101], v[192:193]
	v_pk_fma_f32 v[194:195], v[38:39], v[102:103], v[194:195]
	v_cvt_pk_bf16_f32 v192, v192, v193
	v_cvt_pk_bf16_f32 v193, v194, v195
	global_store_dwordx2 v203, v[192:193], s[30:31] offset:256
	v_pk_fma_f32 v[196:197], v[36:37], v[96:97], v[196:197]
	v_pk_fma_f32 v[198:199], v[38:39], v[98:99], v[198:199]
	v_cvt_pk_bf16_f32 v196, v196, v197
	v_cvt_pk_bf16_f32 v197, v198, v199
	global_store_dwordx2 v203, v[196:197], s[100:101] offset:256
	s_add_u32 s30, s30, 0x8000
	s_addc_u32 s31, s31, 0
	s_add_u32 s100, s100, 0x8000
	s_addc_u32 s101, s101, 0
	global_load_dwordx2 v[96:97], v203, s[24:25]
	global_load_dwordx2 v[98:99], v203, s[26:27]
	global_load_dwordx2 v[100:101], v203, s[24:25] offset:256
	global_load_dwordx2 v[102:103], v203, s[26:27] offset:256
	s_waitcnt lgkmcnt(0)
	ds_read_b128 v[92:95], v221
	ds_read_b128 v[88:91], v221 offset:1024
	s_waitcnt vmcnt(38)
; #define PG8_LAS __attribute__((address_space(3)))
; __device__ __forceinline__ unsigned cvt_pk_bf16(float lo, float hi) { const f32x2c v = {lo, hi}; const bf16x2c b = __builtin_convertvector(v, bf16x2c); return __builtin_bit_cast(unsigned, b); }
;     __device__ __forceinline__ void operator()(const f32x4 (&acc)[2][2][4][2], const Unit& u, int wr, int wc, int fr, int fq) const {
;     ...
;                 const int r0 = u.pm * BM + ai * HALF + wr * 64 + m * 16;
;                 f32x2 st2[2];
; #pragma unroll
;                 for (int s = 0; s < 2; ++s) { st2[s] = (f32x2){0.f, 1.f}; if (mode) st2[s] = *(const PG8_GAS f32x2*)(stats + 2 * (size_t)(r0 + 8 * s + rrow)); }
; #pragma unroll
;                 for (int bj = 0; bj < 2; ++bj) {
;                     const size_t off0 = (size_t)(r0 + rrow) * 1024 + u.pn * BM + bj * HALF + wc * 32 + 4 * rch;
;                     f32x4 xo[2];
; #pragma unroll
;                     for (int s = 0; s < 2; ++s) {
;                         if (!mode) xo[s] = *(const PG8_GAS f32x4*)(xin + off0 + (size_t)s * 8192);
;                         else { const u32x2 w = *(const PG8_GAS u32x2*)(Z + off0 + (size_t)s * 8192);
;                             xo[s] = (f32x4){__builtin_bit_cast(float, w.x << 16), __builtin_bit_cast(float, w.x & 0xffff0000u), __builtin_bit_cast(float, w.y << 16), __builtin_bit_cast(float, w.y & 0xffff0000u)}; }
;                     }
; #pragma unroll
;                     for (int n = 0; n < 2; ++n) *(PG8_LAS f32x4*)(sw + wrow + (((4 * n + fq) ^ (fr & 7)) << 4)) = acc[ai][bj][m][n];
;                     asm volatile("s_waitcnt lgkmcnt(0)" ::: "memory");
;                     f32x4 av[2];
; #pragma unroll
;                     for (int s = 0; s < 2; ++s) av[s] = *(const PG8_LAS f32x4*)(sw + (8 * s + rrow) * 128 + ((rch ^ ((8 * s + rrow) & 7)) << 4));
;                     asm volatile("s_waitcnt lgkmcnt(0)" ::: "memory");
; #pragma unroll
;                     for (int s = 0; s < 2; ++s) {
;                         f32x4 xv = xo[s];
;                         if (mode) xv = (xv - st2[s].x) * st2[s].y * lg[bj] + lb[bj];
;                         const f32x4 zz = xv * alpha + gt[bj] * av[s];
;                         u32x2 zp; zp.x = cvt_pk_bf16(zz.x, zz.y); zp.y = cvt_pk_bf16(zz.z, zz.w);
;                         *(PG8_GAS u32x2*)(Z + off0 + (size_t)s * 8192) = zp;
;                     }
	v_lshlrev_b32_e32 v192, 16, v244
	v_and_b32_e32 v193, 0xffff0000, v244
	v_lshlrev_b32_e32 v194, 16, v245
	v_and_b32_e32 v195, 0xffff0000, v245
	v_sub_f32_e32 v192, v192, v188
	v_sub_f32_e32 v193, v193, v188
	v_sub_f32_e32 v194, v194, v188
	v_sub_f32_e32 v195, v195, v188
	v_pk_mul_f32 v[192:193], v[188:189], v[192:193] op_sel:[1,0]
	v_pk_mul_f32 v[194:195], v[188:189], v[194:195] op_sel:[1,0]
	v_pk_fma_f32 v[192:193], v[48:49], v[192:193], v[144:145]
	v_pk_fma_f32 v[194:195], v[50:51], v[194:195], v[146:147]
	v_pk_mul_f32 v[192:193], v[192:193], s[46:47] op_sel_hi:[1,0]
	v_pk_mul_f32 v[194:195], v[194:195], s[46:47] op_sel_hi:[1,0]
	v_lshlrev_b32_e32 v196, 16, v246
	v_and_b32_e32 v197, 0xffff0000, v246
	v_lshlrev_b32_e32 v198, 16, v247
	v_and_b32_e32 v199, 0xffff0000, v247
	v_sub_f32_e32 v196, v196, v190
	v_sub_f32_e32 v197, v197, v190
	v_sub_f32_e32 v198, v198, v190
	v_sub_f32_e32 v199, v199, v190
	v_pk_mul_f32 v[196:197], v[190:191], v[196:197] op_sel:[1,0]
	v_pk_mul_f32 v[198:199], v[190:191], v[198:199] op_sel:[1,0]
	v_pk_fma_f32 v[196:197], v[48:49], v[196:197], v[144:145]
	v_pk_fma_f32 v[198:199], v[50:51], v[198:199], v[146:147]
	v_pk_mul_f32 v[196:197], v[196:197], s[46:47] op_sel_hi:[1,0]
	v_pk_mul_f32 v[198:199], v[198:199], s[46:47] op_sel_hi:[1,0]
	s_waitcnt lgkmcnt(0)
	ds_write_b128 v219, v[84:87]
	ds_write_b128 v220, v[80:83]
	v_pk_fma_f32 v[192:193], v[32:33], v[92:93], v[192:193]
	v_pk_fma_f32 v[194:195], v[34:35], v[94:95], v[194:195]
	v_cvt_pk_bf16_f32 v192, v192, v193
	v_cvt_pk_bf16_f32 v193, v194, v195
	global_store_dwordx2 v203, v[192:193], s[30:31]
	v_pk_fma_f32 v[196:197], v[32:33], v[88:89], v[196:197]
	v_pk_fma_f32 v[198:199], v[34:35], v[90:91], v[198:199]
	v_cvt_pk_bf16_f32 v196, v196, v197
	v_cvt_pk_bf16_f32 v197, v198, v199
	global_store_dwordx2 v203, v[196:197], s[100:101]
	s_waitcnt lgkmcnt(0)
	ds_read_b128 v[84:87], v221
	ds_read_b128 v[80:83], v221 offset:1024
	s_waitcnt vmcnt(38)
	v_lshlrev_b32_e32 v192, 16, v248
	v_and_b32_e32 v193, 0xffff0000, v248
	v_lshlrev_b32_e32 v194, 16, v249
	v_and_b32_e32 v195, 0xffff0000, v249
	v_sub_f32_e32 v192, v192, v188
	v_sub_f32_e32 v193, v193, v188
	v_sub_f32_e32 v194, v194, v188
	v_sub_f32_e32 v195, v195, v188
	v_pk_mul_f32 v[192:193], v[188:189], v[192:193] op_sel:[1,0]
	v_pk_mul_f32 v[194:195], v[188:189], v[194:195] op_sel:[1,0]
	v_pk_fma_f32 v[192:193], v[52:53], v[192:193], v[148:149]
	v_pk_fma_f32 v[194:195], v[54:55], v[194:195], v[150:151]
	v_pk_mul_f32 v[192:193], v[192:193], s[46:47] op_sel_hi:[1,0]
	v_pk_mul_f32 v[194:195], v[194:195], s[46:47] op_sel_hi:[1,0]
	v_lshlrev_b32_e32 v196, 16, v250
	v_and_b32_e32 v197, 0xffff0000, v250
	v_lshlrev_b32_e32 v198, 16, v251
	v_and_b32_e32 v199, 0xffff0000, v251
	v_sub_f32_e32 v196, v196, v190
	v_sub_f32_e32 v197, v197, v190
	v_sub_f32_e32 v198, v198, v190
	v_sub_f32_e32 v199, v199, v190
	v_pk_mul_f32 v[196:197], v[190:191], v[196:197] op_sel:[1,0]
	v_pk_mul_f32 v[198:199], v[190:191], v[198:199] op_sel:[1,0]
	v_pk_fma_f32 v[196:197], v[52:53], v[196:197], v[148:149]
	v_pk_fma_f32 v[198:199], v[54:55], v[198:199], v[150:151]
	v_pk_mul_f32 v[196:197], v[196:197], s[46:47] op_sel_hi:[1,0]
	v_pk_mul_f32 v[198:199], v[198:199], s[46:47] op_sel_hi:[1,0]
	s_waitcnt lgkmcnt(0)
	ds_write_b128 v219, v[76:79]
	ds_write_b128 v220, v[72:75]
	v_pk_fma_f32 v[192:193], v[36:37], v[84:85], v[192:193]
	v_pk_fma_f32 v[194:195], v[38:39], v[86:87], v[194:195]
	v_cvt_pk_bf16_f32 v192, v192, v193
	v_cvt_pk_bf16_f32 v193, v194, v195
	global_store_dwordx2 v203, v[192:193], s[30:31] offset:256
	v_pk_fma_f32 v[196:197], v[36:37], v[80:81], v[196:197]
	v_pk_fma_f32 v[198:199], v[38:39], v[82:83], v[198:199]
	v_cvt_pk_bf16_f32 v196, v196, v197
	v_cvt_pk_bf16_f32 v197, v198, v199
	global_store_dwordx2 v203, v[196:197], s[100:101] offset:256
	s_add_u32 s30, s30, 0x28000
	s_addc_u32 s31, s31, 0
	s_add_u32 s100, s100, 0x28000
	s_addc_u32 s101, s101, 0
	s_waitcnt lgkmcnt(0)
	ds_read_b128 v[76:79], v221
	ds_read_b128 v[72:75], v221 offset:1024
	s_waitcnt vmcnt(24)
	v_lshlrev_b32_e32 v192, 16, v120
	v_and_b32_e32 v193, 0xffff0000, v120
	v_lshlrev_b32_e32 v194, 16, v121
	v_and_b32_e32 v195, 0xffff0000, v121
	v_sub_f32_e32 v192, v192, v136
	v_sub_f32_e32 v193, v193, v136
	v_sub_f32_e32 v194, v194, v136
	v_sub_f32_e32 v195, v195, v136
	v_pk_mul_f32 v[192:193], v[136:137], v[192:193] op_sel:[1,0]
	v_pk_mul_f32 v[194:195], v[136:137], v[194:195] op_sel:[1,0]
	v_pk_fma_f32 v[192:193], v[48:49], v[192:193], v[144:145]
	v_pk_fma_f32 v[194:195], v[50:51], v[194:195], v[146:147]
	v_pk_mul_f32 v[192:193], v[192:193], s[46:47] op_sel_hi:[1,0]
	v_pk_mul_f32 v[194:195], v[194:195], s[46:47] op_sel_hi:[1,0]
	v_lshlrev_b32_e32 v196, 16, v122
	v_and_b32_e32 v197, 0xffff0000, v122
	v_lshlrev_b32_e32 v198, 16, v123
	v_and_b32_e32 v199, 0xffff0000, v123
	v_sub_f32_e32 v196, v196, v138
	v_sub_f32_e32 v197, v197, v138
	v_sub_f32_e32 v198, v198, v138
	v_sub_f32_e32 v199, v199, v138
	v_pk_mul_f32 v[196:197], v[138:139], v[196:197] op_sel:[1,0]
	v_pk_mul_f32 v[198:199], v[138:139], v[198:199] op_sel:[1,0]
	v_pk_fma_f32 v[196:197], v[48:49], v[196:197], v[144:145]
	v_pk_fma_f32 v[198:199], v[50:51], v[198:199], v[146:147]
	v_pk_mul_f32 v[196:197], v[196:197], s[46:47] op_sel_hi:[1,0]
	v_pk_mul_f32 v[198:199], v[198:199], s[46:47] op_sel_hi:[1,0]
	s_waitcnt lgkmcnt(0)
	ds_write_b128 v219, v[68:71]
	ds_write_b128 v220, v[64:67]
	v_pk_fma_f32 v[192:193], v[32:33], v[76:77], v[192:193]
	v_pk_fma_f32 v[194:195], v[34:35], v[78:79], v[194:195]
	v_cvt_pk_bf16_f32 v192, v192, v193
	v_cvt_pk_bf16_f32 v193, v194, v195
	global_store_dwordx2 v203, v[192:193], s[30:31]
	v_pk_fma_f32 v[196:197], v[32:33], v[72:73], v[196:197]
	v_pk_fma_f32 v[198:199], v[34:35], v[74:75], v[198:199]
	v_cvt_pk_bf16_f32 v196, v196, v197
	v_cvt_pk_bf16_f32 v197, v198, v199
	global_store_dwordx2 v203, v[196:197], s[100:101]
	s_waitcnt lgkmcnt(0)
; #define PG8_LAS __attribute__((address_space(3)))
; __device__ __forceinline__ unsigned cvt_pk_bf16(float lo, float hi) { const f32x2c v = {lo, hi}; const bf16x2c b = __builtin_convertvector(v, bf16x2c); return __builtin_bit_cast(unsigned, b); }
;     __device__ __forceinline__ void operator()(const f32x4 (&acc)[2][2][4][2], const Unit& u, int wr, int wc, int fr, int fq) const {
;     ...
;                 const int r0 = u.pm * BM + ai * HALF + wr * 64 + m * 16;
;                 f32x2 st2[2];
; #pragma unroll
;                 for (int s = 0; s < 2; ++s) { st2[s] = (f32x2){0.f, 1.f}; if (mode) st2[s] = *(const PG8_GAS f32x2*)(stats + 2 * (size_t)(r0 + 8 * s + rrow)); }
; #pragma unroll
;                 for (int bj = 0; bj < 2; ++bj) {
;                     const size_t off0 = (size_t)(r0 + rrow) * 1024 + u.pn * BM + bj * HALF + wc * 32 + 4 * rch;
;                     f32x4 xo[2];
; #pragma unroll
;                     for (int s = 0; s < 2; ++s) {
;                         if (!mode) xo[s] = *(const PG8_GAS f32x4*)(xin + off0 + (size_t)s * 8192);
;                         else { const u32x2 w = *(const PG8_GAS u32x2*)(Z + off0 + (size_t)s * 8192);
;                             xo[s] = (f32x4){__builtin_bit_cast(float, w.x << 16), __builtin_bit_cast(float, w.x & 0xffff0000u), __builtin_bit_cast(float, w.y << 16), __builtin_bit_cast(float, w.y & 0xffff0000u)}; }
;                     }
; #pragma unroll
;                     for (int n = 0; n < 2; ++n) *(PG8_LAS f32x4*)(sw + wrow + (((4 * n + fq) ^ (fr & 7)) << 4)) = acc[ai][bj][m][n];
;                     asm volatile("s_waitcnt lgkmcnt(0)" ::: "memory");
;                     f32x4 av[2];
; #pragma unroll
;                     for (int s = 0; s < 2; ++s) av[s] = *(const PG8_LAS f32x4*)(sw + (8 * s + rrow) * 128 + ((rch ^ ((8 * s + rrow) & 7)) << 4));
;                     asm volatile("s_waitcnt lgkmcnt(0)" ::: "memory");
; #pragma unroll
;                     for (int s = 0; s < 2; ++s) {
;                         f32x4 xv = xo[s];
;                         if (mode) xv = (xv - st2[s].x) * st2[s].y * lg[bj] + lb[bj];
;                         const f32x4 zz = xv * alpha + gt[bj] * av[s];
;                         u32x2 zp; zp.x = cvt_pk_bf16(zz.x, zz.y); zp.y = cvt_pk_bf16(zz.z, zz.w);
;                         *(PG8_GAS u32x2*)(Z + off0 + (size_t)s * 8192) = zp;
;                     }
	ds_read_b128 v[68:71], v221
	ds_read_b128 v[64:67], v221 offset:1024
	s_waitcnt vmcnt(24)
	v_lshlrev_b32_e32 v192, 16, v124
	v_and_b32_e32 v193, 0xffff0000, v124
	v_lshlrev_b32_e32 v194, 16, v125
	v_and_b32_e32 v195, 0xffff0000, v125
	v_sub_f32_e32 v192, v192, v136
	v_sub_f32_e32 v193, v193, v136
	v_sub_f32_e32 v194, v194, v136
	v_sub_f32_e32 v195, v195, v136
	v_pk_mul_f32 v[192:193], v[136:137], v[192:193] op_sel:[1,0]
	v_pk_mul_f32 v[194:195], v[136:137], v[194:195] op_sel:[1,0]
	v_pk_fma_f32 v[192:193], v[52:53], v[192:193], v[148:149]
	v_pk_fma_f32 v[194:195], v[54:55], v[194:195], v[150:151]
	v_pk_mul_f32 v[192:193], v[192:193], s[46:47] op_sel_hi:[1,0]
	v_pk_mul_f32 v[194:195], v[194:195], s[46:47] op_sel_hi:[1,0]
	v_lshlrev_b32_e32 v196, 16, v126
	v_and_b32_e32 v197, 0xffff0000, v126
	v_lshlrev_b32_e32 v198, 16, v127
	v_and_b32_e32 v199, 0xffff0000, v127
	v_sub_f32_e32 v196, v196, v138
	v_sub_f32_e32 v197, v197, v138
	v_sub_f32_e32 v198, v198, v138
	v_sub_f32_e32 v199, v199, v138
	v_pk_mul_f32 v[196:197], v[138:139], v[196:197] op_sel:[1,0]
	v_pk_mul_f32 v[198:199], v[138:139], v[198:199] op_sel:[1,0]
	v_pk_fma_f32 v[196:197], v[52:53], v[196:197], v[148:149]
	v_pk_fma_f32 v[198:199], v[54:55], v[198:199], v[150:151]
	v_pk_mul_f32 v[196:197], v[196:197], s[46:47] op_sel_hi:[1,0]
	v_pk_mul_f32 v[198:199], v[198:199], s[46:47] op_sel_hi:[1,0]
	s_waitcnt lgkmcnt(0)
	ds_write_b128 v219, v[60:63]
	ds_write_b128 v220, v[56:59]
	v_pk_fma_f32 v[192:193], v[36:37], v[68:69], v[192:193]
	v_pk_fma_f32 v[194:195], v[38:39], v[70:71], v[194:195]
	v_cvt_pk_bf16_f32 v192, v192, v193
	v_cvt_pk_bf16_f32 v193, v194, v195
	global_store_dwordx2 v203, v[192:193], s[30:31] offset:256
	v_pk_fma_f32 v[196:197], v[36:37], v[64:65], v[196:197]
	v_pk_fma_f32 v[198:199], v[38:39], v[66:67], v[198:199]
	v_cvt_pk_bf16_f32 v196, v196, v197
	v_cvt_pk_bf16_f32 v197, v198, v199
	global_store_dwordx2 v203, v[196:197], s[100:101] offset:256
	s_add_u32 s30, s30, 0x8000
	s_addc_u32 s31, s31, 0
	s_add_u32 s100, s100, 0x8000
	s_addc_u32 s101, s101, 0
	s_waitcnt lgkmcnt(0)
	ds_read_b128 v[60:63], v221
	ds_read_b128 v[56:59], v221 offset:1024
	s_waitcnt vmcnt(22)
	v_lshlrev_b32_e32 v192, 16, v112
	v_and_b32_e32 v193, 0xffff0000, v112
	v_lshlrev_b32_e32 v194, 16, v113
	v_and_b32_e32 v195, 0xffff0000, v113
	v_sub_f32_e32 v192, v192, v140
	v_sub_f32_e32 v193, v193, v140
	v_sub_f32_e32 v194, v194, v140
	v_sub_f32_e32 v195, v195, v140
	v_pk_mul_f32 v[192:193], v[140:141], v[192:193] op_sel:[1,0]
	v_pk_mul_f32 v[194:195], v[140:141], v[194:195] op_sel:[1,0]
	v_pk_fma_f32 v[192:193], v[48:49], v[192:193], v[144:145]
	v_pk_fma_f32 v[194:195], v[50:51], v[194:195], v[146:147]
	v_pk_mul_f32 v[192:193], v[192:193], s[46:47] op_sel_hi:[1,0]
	v_pk_mul_f32 v[194:195], v[194:195], s[46:47] op_sel_hi:[1,0]
	v_lshlrev_b32_e32 v196, 16, v114
	v_and_b32_e32 v197, 0xffff0000, v114
	v_lshlrev_b32_e32 v198, 16, v115
	v_and_b32_e32 v199, 0xffff0000, v115
	v_sub_f32_e32 v196, v196, v142
	v_sub_f32_e32 v197, v197, v142
	v_sub_f32_e32 v198, v198, v142
	v_sub_f32_e32 v199, v199, v142
	v_pk_mul_f32 v[196:197], v[142:143], v[196:197] op_sel:[1,0]
	v_pk_mul_f32 v[198:199], v[142:143], v[198:199] op_sel:[1,0]
	v_pk_fma_f32 v[196:197], v[48:49], v[196:197], v[144:145]
	v_pk_fma_f32 v[198:199], v[50:51], v[198:199], v[146:147]
	v_pk_mul_f32 v[196:197], v[196:197], s[46:47] op_sel_hi:[1,0]
	v_pk_mul_f32 v[198:199], v[198:199], s[46:47] op_sel_hi:[1,0]
	s_waitcnt lgkmcnt(0)
	ds_write_b128 v219, v[44:47]
	ds_write_b128 v220, v[40:43]
	v_pk_fma_f32 v[192:193], v[32:33], v[60:61], v[192:193]
	v_pk_fma_f32 v[194:195], v[34:35], v[62:63], v[194:195]
	v_cvt_pk_bf16_f32 v192, v192, v193
	v_cvt_pk_bf16_f32 v193, v194, v195
	global_store_dwordx2 v203, v[192:193], s[30:31]
	v_pk_fma_f32 v[196:197], v[32:33], v[56:57], v[196:197]
	v_pk_fma_f32 v[198:199], v[34:35], v[58:59], v[198:199]
	v_cvt_pk_bf16_f32 v196, v196, v197
	v_cvt_pk_bf16_f32 v197, v198, v199
	global_store_dwordx2 v203, v[196:197], s[100:101]
	s_waitcnt lgkmcnt(0)
	ds_read_b128 v[44:47], v221
	ds_read_b128 v[40:43], v221 offset:1024
	s_waitcnt vmcnt(22)
	v_lshlrev_b32_e32 v192, 16, v116
	v_and_b32_e32 v193, 0xffff0000, v116
	v_lshlrev_b32_e32 v194, 16, v117
	v_and_b32_e32 v195, 0xffff0000, v117
	v_sub_f32_e32 v192, v192, v140
	v_sub_f32_e32 v193, v193, v140
	v_sub_f32_e32 v194, v194, v140
	v_sub_f32_e32 v195, v195, v140
	v_pk_mul_f32 v[192:193], v[140:141], v[192:193] op_sel:[1,0]
	v_pk_mul_f32 v[194:195], v[140:141], v[194:195] op_sel:[1,0]
	v_pk_fma_f32 v[192:193], v[52:53], v[192:193], v[148:149]
	v_pk_fma_f32 v[194:195], v[54:55], v[194:195], v[150:151]
	v_pk_mul_f32 v[192:193], v[192:193], s[46:47] op_sel_hi:[1,0]
	v_pk_mul_f32 v[194:195], v[194:195], s[46:47] op_sel_hi:[1,0]
	v_lshlrev_b32_e32 v196, 16, v118
	v_and_b32_e32 v197, 0xffff0000, v118
	v_lshlrev_b32_e32 v198, 16, v119
	v_and_b32_e32 v199, 0xffff0000, v119
	v_sub_f32_e32 v196, v196, v142
	v_sub_f32_e32 v197, v197, v142
	v_sub_f32_e32 v198, v198, v142
	v_sub_f32_e32 v199, v199, v142
	v_pk_mul_f32 v[196:197], v[142:143], v[196:197] op_sel:[1,0]
	v_pk_mul_f32 v[198:199], v[142:143], v[198:199] op_sel:[1,0]
	v_pk_fma_f32 v[196:197], v[52:53], v[196:197], v[148:149]
	v_pk_fma_f32 v[198:199], v[54:55], v[198:199], v[150:151]
	v_pk_mul_f32 v[196:197], v[196:197], s[46:47] op_sel_hi:[1,0]
	v_pk_mul_f32 v[198:199], v[198:199], s[46:47] op_sel_hi:[1,0]
	s_waitcnt lgkmcnt(0)
; #define PG8_LAS __attribute__((address_space(3)))
; __device__ __forceinline__ unsigned cvt_pk_bf16(float lo, float hi) { const f32x2c v = {lo, hi}; const bf16x2c b = __builtin_convertvector(v, bf16x2c); return __builtin_bit_cast(unsigned, b); }
;     __device__ __forceinline__ void operator()(const f32x4 (&acc)[2][2][4][2], const Unit& u, int wr, int wc, int fr, int fq) const {
;     ...
;                 const int r0 = u.pm * BM + ai * HALF + wr * 64 + m * 16;
;                 f32x2 st2[2];
; #pragma unroll
;                 for (int s = 0; s < 2; ++s) { st2[s] = (f32x2){0.f, 1.f}; if (mode) st2[s] = *(const PG8_GAS f32x2*)(stats + 2 * (size_t)(r0 + 8 * s + rrow)); }
; #pragma unroll
;                 for (int bj = 0; bj < 2; ++bj) {
;                     const size_t off0 = (size_t)(r0 + rrow) * 1024 + u.pn * BM + bj * HALF + wc * 32 + 4 * rch;
;                     f32x4 xo[2];
; #pragma unroll
;                     for (int s = 0; s < 2; ++s) {
;                         if (!mode) xo[s] = *(const PG8_GAS f32x4*)(xin + off0 + (size_t)s * 8192);
;                         else { const u32x2 w = *(const PG8_GAS u32x2*)(Z + off0 + (size_t)s * 8192);
;                             xo[s] = (f32x4){__builtin_bit_cast(float, w.x << 16), __builtin_bit_cast(float, w.x & 0xffff0000u), __builtin_bit_cast(float, w.y << 16), __builtin_bit_cast(float, w.y & 0xffff0000u)}; }
;                     }
; #pragma unroll
;                     for (int n = 0; n < 2; ++n) *(PG8_LAS f32x4*)(sw + wrow + (((4 * n + fq) ^ (fr & 7)) << 4)) = acc[ai][bj][m][n];
;                     asm volatile("s_waitcnt lgkmcnt(0)" ::: "memory");
;                     f32x4 av[2];
; #pragma unroll
;                     for (int s = 0; s < 2; ++s) av[s] = *(const PG8_LAS f32x4*)(sw + (8 * s + rrow) * 128 + ((rch ^ ((8 * s + rrow) & 7)) << 4));
;                     asm volatile("s_waitcnt lgkmcnt(0)" ::: "memory");
; #pragma unroll
;                     for (int s = 0; s < 2; ++s) {
;                         f32x4 xv = xo[s];
;                         if (mode) xv = (xv - st2[s].x) * st2[s].y * lg[bj] + lb[bj];
;                         const f32x4 zz = xv * alpha + gt[bj] * av[s];
;                         u32x2 zp; zp.x = cvt_pk_bf16(zz.x, zz.y); zp.y = cvt_pk_bf16(zz.z, zz.w);
;                         *(PG8_GAS u32x2*)(Z + off0 + (size_t)s * 8192) = zp;
;                     }
	ds_write_b128 v219, v[28:31]
	ds_write_b128 v220, v[24:27]
	v_pk_fma_f32 v[192:193], v[36:37], v[44:45], v[192:193]
	v_pk_fma_f32 v[194:195], v[38:39], v[46:47], v[194:195]
	v_cvt_pk_bf16_f32 v192, v192, v193
	v_cvt_pk_bf16_f32 v193, v194, v195
	global_store_dwordx2 v203, v[192:193], s[30:31] offset:256
	v_pk_fma_f32 v[196:197], v[36:37], v[40:41], v[196:197]
	v_pk_fma_f32 v[198:199], v[38:39], v[42:43], v[198:199]
	v_cvt_pk_bf16_f32 v196, v196, v197
	v_cvt_pk_bf16_f32 v197, v198, v199
	global_store_dwordx2 v203, v[196:197], s[100:101] offset:256
	s_add_u32 s30, s30, 0x8000
	s_addc_u32 s31, s31, 0
	s_add_u32 s100, s100, 0x8000
	s_addc_u32 s101, s101, 0
	s_waitcnt lgkmcnt(0)
	ds_read_b128 v[28:31], v221
	ds_read_b128 v[24:27], v221 offset:1024
	s_waitcnt vmcnt(20)
	v_lshlrev_b32_e32 v192, 16, v104
	v_and_b32_e32 v193, 0xffff0000, v104
	v_lshlrev_b32_e32 v194, 16, v105
	v_and_b32_e32 v195, 0xffff0000, v105
	v_sub_f32_e32 v192, v192, v128
	v_sub_f32_e32 v193, v193, v128
	v_sub_f32_e32 v194, v194, v128
	v_sub_f32_e32 v195, v195, v128
	v_pk_mul_f32 v[192:193], v[128:129], v[192:193] op_sel:[1,0]
	v_pk_mul_f32 v[194:195], v[128:129], v[194:195] op_sel:[1,0]
	v_pk_fma_f32 v[192:193], v[48:49], v[192:193], v[144:145]
	v_pk_fma_f32 v[194:195], v[50:51], v[194:195], v[146:147]
	v_pk_mul_f32 v[192:193], v[192:193], s[46:47] op_sel_hi:[1,0]
	v_pk_mul_f32 v[194:195], v[194:195], s[46:47] op_sel_hi:[1,0]
	v_lshlrev_b32_e32 v196, 16, v106
	v_and_b32_e32 v197, 0xffff0000, v106
	v_lshlrev_b32_e32 v198, 16, v107
	v_and_b32_e32 v199, 0xffff0000, v107
	v_sub_f32_e32 v196, v196, v130
	v_sub_f32_e32 v197, v197, v130
	v_sub_f32_e32 v198, v198, v130
	v_sub_f32_e32 v199, v199, v130
	v_pk_mul_f32 v[196:197], v[130:131], v[196:197] op_sel:[1,0]
	v_pk_mul_f32 v[198:199], v[130:131], v[198:199] op_sel:[1,0]
	v_pk_fma_f32 v[196:197], v[48:49], v[196:197], v[144:145]
	v_pk_fma_f32 v[198:199], v[50:51], v[198:199], v[146:147]
	v_pk_mul_f32 v[196:197], v[196:197], s[46:47] op_sel_hi:[1,0]
	v_pk_mul_f32 v[198:199], v[198:199], s[46:47] op_sel_hi:[1,0]
	s_waitcnt lgkmcnt(0)
	ds_write_b128 v219, v[20:23]
	ds_write_b128 v220, v[16:19]
	v_pk_fma_f32 v[192:193], v[32:33], v[28:29], v[192:193]
	v_pk_fma_f32 v[194:195], v[34:35], v[30:31], v[194:195]
	v_cvt_pk_bf16_f32 v192, v192, v193
	v_cvt_pk_bf16_f32 v193, v194, v195
	global_store_dwordx2 v203, v[192:193], s[30:31]
	v_pk_fma_f32 v[196:197], v[32:33], v[24:25], v[196:197]
	v_pk_fma_f32 v[198:199], v[34:35], v[26:27], v[198:199]
	v_cvt_pk_bf16_f32 v196, v196, v197
	v_cvt_pk_bf16_f32 v197, v198, v199
	global_store_dwordx2 v203, v[196:197], s[100:101]
	s_waitcnt lgkmcnt(0)
	ds_read_b128 v[20:23], v221
	ds_read_b128 v[16:19], v221 offset:1024
	s_waitcnt vmcnt(20)
	v_lshlrev_b32_e32 v192, 16, v108
	v_and_b32_e32 v193, 0xffff0000, v108
	v_lshlrev_b32_e32 v194, 16, v109
	v_and_b32_e32 v195, 0xffff0000, v109
	v_sub_f32_e32 v192, v192, v128
	v_sub_f32_e32 v193, v193, v128
	v_sub_f32_e32 v194, v194, v128
	v_sub_f32_e32 v195, v195, v128
	v_pk_mul_f32 v[192:193], v[128:129], v[192:193] op_sel:[1,0]
	v_pk_mul_f32 v[194:195], v[128:129], v[194:195] op_sel:[1,0]
	v_pk_fma_f32 v[192:193], v[52:53], v[192:193], v[148:149]
	v_pk_fma_f32 v[194:195], v[54:55], v[194:195], v[150:151]
	v_pk_mul_f32 v[192:193], v[192:193], s[46:47] op_sel_hi:[1,0]
	v_pk_mul_f32 v[194:195], v[194:195], s[46:47] op_sel_hi:[1,0]
	v_lshlrev_b32_e32 v196, 16, v110
	v_and_b32_e32 v197, 0xffff0000, v110
	v_lshlrev_b32_e32 v198, 16, v111
	v_and_b32_e32 v199, 0xffff0000, v111
	v_sub_f32_e32 v196, v196, v130
	v_sub_f32_e32 v197, v197, v130
	v_sub_f32_e32 v198, v198, v130
	v_sub_f32_e32 v199, v199, v130
	v_pk_mul_f32 v[196:197], v[130:131], v[196:197] op_sel:[1,0]
	v_pk_mul_f32 v[198:199], v[130:131], v[198:199] op_sel:[1,0]
	v_pk_fma_f32 v[196:197], v[52:53], v[196:197], v[148:149]
	v_pk_fma_f32 v[198:199], v[54:55], v[198:199], v[150:151]
	v_pk_mul_f32 v[196:197], v[196:197], s[46:47] op_sel_hi:[1,0]
	v_pk_mul_f32 v[198:199], v[198:199], s[46:47] op_sel_hi:[1,0]
	s_waitcnt lgkmcnt(0)
;     __device__ __forceinline__ void operator()(const f32x4 (&acc)[2][2][4][2], const Unit& u, int wr, int wc, int fr, int fq) const {
;     ...
;                 const int r0 = u.pm * BM + ai * HALF + wr * 64 + m * 16;
;                 f32x2 st2[2];
; #pragma unroll
;                 for (int s = 0; s < 2; ++s) { st2[s] = (f32x2){0.f, 1.f}; if (mode) st2[s] = *(const PG8_GAS f32x2*)(stats + 2 * (size_t)(r0 + 8 * s + rrow)); }
; #pragma unroll
;                 for (int bj = 0; bj < 2; ++bj) {
;                     const size_t off0 = (size_t)(r0 + rrow) * 1024 + u.pn * BM + bj * HALF + wc * 32 + 4 * rch;
;                     f32x4 xo[2];
; #pragma unroll
;                     for (int s = 0; s < 2; ++s) {
;                         if (!mode) xo[s] = *(const PG8_GAS f32x4*)(xin + off0 + (size_t)s * 8192);
;                         else { const u32x2 w = *(const PG8_GAS u32x2*)(Z + off0 + (size_t)s * 8192);
;                             xo[s] = (f32x4){__builtin_bit_cast(float, w.x << 16), __builtin_bit_cast(float, w.x & 0xffff0000u), __builtin_bit_cast(float, w.y << 16), __builtin_bit_cast(float, w.y & 0xffff0000u)}; }
;                     }
; #pragma unroll
;                     for (int n = 0; n < 2; ++n) *(PG8_LAS f32x4*)(sw + wrow + (((4 * n + fq) ^ (fr & 7)) << 4)) = acc[ai][bj][m][n];
;                     asm volatile("s_waitcnt lgkmcnt(0)" ::: "memory");
;                     f32x4 av[2];
; #pragma unroll
;                     for (int s = 0; s < 2; ++s) av[s] = *(const PG8_LAS f32x4*)(sw + (8 * s + rrow) * 128 + ((rch ^ ((8 * s + rrow) & 7)) << 4));
;                     asm volatile("s_waitcnt lgkmcnt(0)" ::: "memory");
; #pragma unroll
;                     for (int s = 0; s < 2; ++s) {
;                         f32x4 xv = xo[s];
;                         if (mode) xv = (xv - st2[s].x) * st2[s].y * lg[bj] + lb[bj];
;                         const f32x4 zz = xv * alpha + gt[bj] * av[s];
;                         u32x2 zp; zp.x = cvt_pk_bf16(zz.x, zz.y); zp.y = cvt_pk_bf16(zz.z, zz.w);
;                         *(PG8_GAS u32x2*)(Z + off0 + (size_t)s * 8192) = zp;
;                     }
; template <class Epi, class Sched, bool ALIGN_EPI = false, bool SP2 = false>
; __device__ __forceinline__ void gemm_phase(PG8_LAS unsigned char* lds, const Gemm g, const Sched& S, const Epi& E, const int tid) {
;     ...
;         if (!has_next) break;
	ds_write_b128 v219, v[12:15]
	ds_write_b128 v220, v[8:11]
	v_pk_fma_f32 v[192:193], v[36:37], v[20:21], v[192:193]
	v_pk_fma_f32 v[194:195], v[38:39], v[22:23], v[194:195]
	v_cvt_pk_bf16_f32 v192, v192, v193
	v_cvt_pk_bf16_f32 v193, v194, v195
	global_store_dwordx2 v203, v[192:193], s[30:31] offset:256
	v_pk_fma_f32 v[196:197], v[36:37], v[16:17], v[196:197]
	v_pk_fma_f32 v[198:199], v[38:39], v[18:19], v[198:199]
	v_cvt_pk_bf16_f32 v196, v196, v197
	v_cvt_pk_bf16_f32 v197, v198, v199
	global_store_dwordx2 v203, v[196:197], s[100:101] offset:256
	s_add_u32 s30, s30, 0x8000
	s_addc_u32 s31, s31, 0
	s_add_u32 s100, s100, 0x8000
	s_addc_u32 s101, s101, 0
	s_waitcnt lgkmcnt(0)
	ds_read_b128 v[12:15], v221
	ds_read_b128 v[8:11], v221 offset:1024
	s_waitcnt vmcnt(18)
	v_lshlrev_b32_e32 v192, 16, v96
	v_and_b32_e32 v193, 0xffff0000, v96
	v_lshlrev_b32_e32 v194, 16, v97
	v_and_b32_e32 v195, 0xffff0000, v97
	v_sub_f32_e32 v192, v192, v132
	v_sub_f32_e32 v193, v193, v132
	v_sub_f32_e32 v194, v194, v132
	v_sub_f32_e32 v195, v195, v132
	v_pk_mul_f32 v[192:193], v[132:133], v[192:193] op_sel:[1,0]
	v_pk_mul_f32 v[194:195], v[132:133], v[194:195] op_sel:[1,0]
	v_pk_fma_f32 v[192:193], v[48:49], v[192:193], v[144:145]
	v_pk_fma_f32 v[194:195], v[50:51], v[194:195], v[146:147]
	v_pk_mul_f32 v[192:193], v[192:193], s[46:47] op_sel_hi:[1,0]
	v_pk_mul_f32 v[194:195], v[194:195], s[46:47] op_sel_hi:[1,0]
	v_lshlrev_b32_e32 v196, 16, v98
	v_and_b32_e32 v197, 0xffff0000, v98
	v_lshlrev_b32_e32 v198, 16, v99
	v_and_b32_e32 v199, 0xffff0000, v99
	v_sub_f32_e32 v196, v196, v134
	v_sub_f32_e32 v197, v197, v134
	v_sub_f32_e32 v198, v198, v134
	v_sub_f32_e32 v199, v199, v134
	v_pk_mul_f32 v[196:197], v[134:135], v[196:197] op_sel:[1,0]
	v_pk_mul_f32 v[198:199], v[134:135], v[198:199] op_sel:[1,0]
	v_pk_fma_f32 v[196:197], v[48:49], v[196:197], v[144:145]
	v_pk_fma_f32 v[198:199], v[50:51], v[198:199], v[146:147]
	v_pk_mul_f32 v[196:197], v[196:197], s[46:47] op_sel_hi:[1,0]
	v_pk_mul_f32 v[198:199], v[198:199], s[46:47] op_sel_hi:[1,0]
	s_waitcnt lgkmcnt(0)
	ds_write_b128 v219, v[4:7]
	ds_write_b128 v220, v[0:3]
	v_pk_fma_f32 v[192:193], v[32:33], v[12:13], v[192:193]
	v_pk_fma_f32 v[194:195], v[34:35], v[14:15], v[194:195]
	v_cvt_pk_bf16_f32 v192, v192, v193
	v_cvt_pk_bf16_f32 v193, v194, v195
	global_store_dwordx2 v203, v[192:193], s[30:31]
	v_pk_fma_f32 v[196:197], v[32:33], v[8:9], v[196:197]
	v_pk_fma_f32 v[198:199], v[34:35], v[10:11], v[198:199]
	v_cvt_pk_bf16_f32 v196, v196, v197
	v_cvt_pk_bf16_f32 v197, v198, v199
	global_store_dwordx2 v203, v[196:197], s[100:101]
	s_waitcnt lgkmcnt(0)
	ds_read_b128 v[4:7], v221
	ds_read_b128 v[0:3], v221 offset:1024
	s_waitcnt vmcnt(18)
	v_lshlrev_b32_e32 v192, 16, v100
	v_and_b32_e32 v193, 0xffff0000, v100
	v_lshlrev_b32_e32 v194, 16, v101
	v_and_b32_e32 v195, 0xffff0000, v101
	v_sub_f32_e32 v192, v192, v132
	v_sub_f32_e32 v193, v193, v132
	v_sub_f32_e32 v194, v194, v132
	v_sub_f32_e32 v195, v195, v132
	v_pk_mul_f32 v[192:193], v[132:133], v[192:193] op_sel:[1,0]
	v_pk_mul_f32 v[194:195], v[132:133], v[194:195] op_sel:[1,0]
	v_pk_fma_f32 v[192:193], v[52:53], v[192:193], v[148:149]
	v_pk_fma_f32 v[194:195], v[54:55], v[194:195], v[150:151]
	v_pk_mul_f32 v[192:193], v[192:193], s[46:47] op_sel_hi:[1,0]
	v_pk_mul_f32 v[194:195], v[194:195], s[46:47] op_sel_hi:[1,0]
	v_lshlrev_b32_e32 v196, 16, v102
	v_and_b32_e32 v197, 0xffff0000, v102
	v_lshlrev_b32_e32 v198, 16, v103
	v_and_b32_e32 v199, 0xffff0000, v103
	v_sub_f32_e32 v196, v196, v134
	v_sub_f32_e32 v197, v197, v134
	v_sub_f32_e32 v198, v198, v134
	v_sub_f32_e32 v199, v199, v134
	v_pk_mul_f32 v[196:197], v[134:135], v[196:197] op_sel:[1,0]
	v_pk_mul_f32 v[198:199], v[134:135], v[198:199] op_sel:[1,0]
	v_pk_fma_f32 v[196:197], v[52:53], v[196:197], v[148:149]
	v_pk_fma_f32 v[198:199], v[54:55], v[198:199], v[150:151]
	v_pk_mul_f32 v[196:197], v[196:197], s[46:47] op_sel_hi:[1,0]
	v_pk_mul_f32 v[198:199], v[198:199], s[46:47] op_sel_hi:[1,0]
	s_waitcnt lgkmcnt(0)
	v_pk_fma_f32 v[192:193], v[36:37], v[4:5], v[192:193]
	v_pk_fma_f32 v[194:195], v[38:39], v[6:7], v[194:195]
	v_cvt_pk_bf16_f32 v192, v192, v193
	v_cvt_pk_bf16_f32 v193, v194, v195
	global_store_dwordx2 v203, v[192:193], s[30:31] offset:256
	v_pk_fma_f32 v[196:197], v[36:37], v[0:1], v[196:197]
	v_pk_fma_f32 v[198:199], v[38:39], v[2:3], v[198:199]
	v_cvt_pk_bf16_f32 v196, v196, v197
	v_cvt_pk_bf16_f32 v197, v198, v199
	global_store_dwordx2 v203, v[196:197], s[100:101] offset:256
	s_and_b64 vcc, exec, s[6:7]
	s_mov_b64 s[6:7], -1
	s_cbranch_vccnz .LBB0_1293
	s_branch .Lres_hasnext

; #define PG8_BAR __builtin_amdgcn_s_barrier()
; template <class Epi, class Sched, bool ALIGN_EPI = false, bool SP2 = false>
; __device__ __forceinline__ void gemm_phase(PG8_LAS unsigned char* lds, const Gemm g, const Sched& S, const Epi& E, const int tid) {
;     ...
;         if (!has_next) break;
; #pragma unroll
;         for (int a = 0; a < 2; ++a)
; #pragma unroll
;             for (int b = 0; b < 2; ++b)
; #pragma unroll
;                 for (int m = 0; m < 4; ++m)
; #pragma unroll
;                     for (int n = 0; n < 2; ++n) acc[a][b][m][n] = (f32x4){0.f, 0.f, 0.f, 0.f};
;         cur = nxt; cA = nA; cB = nB; ++ui;
;         if constexpr (ALIGN_EPI) { if (wr == 1) PG8_BAR; }
.Lres_hasnext:
	s_andn2_b64 vcc, exec, s[10:11]
	s_cbranch_vccnz .LBB0_1292
	s_barrier
	s_branch .LBB0_1292

; __global__ void __launch_bounds__(512, 2) mk_fwd(Args a) {
	.amdhsa_kernel _Z6mk_fwd4Args
		.amdhsa_group_segment_fixed_size 0
		.amdhsa_private_segment_fixed_size 0
		.amdhsa_kernarg_size 432
		.amdhsa_user_sgpr_count 2
		.amdhsa_user_sgpr_dispatch_ptr 0
		.amdhsa_user_sgpr_queue_ptr 0
		.amdhsa_user_sgpr_kernarg_segment_ptr 1
		.amdhsa_user_sgpr_dispatch_id 0
		.amdhsa_user_sgpr_kernarg_preload_length 0
		.amdhsa_user_sgpr_kernarg_preload_offset 0
		.amdhsa_user_sgpr_private_segment_size 0
		.amdhsa_uses_dynamic_stack 0
		.amdhsa_enable_private_segment 0
		.amdhsa_system_sgpr_workgroup_id_x 1
		.amdhsa_system_sgpr_workgroup_id_y 0
		.amdhsa_system_sgpr_workgroup_id_z 0
		.amdhsa_system_sgpr_workgroup_info 0
		.amdhsa_system_vgpr_workitem_id 2
		.amdhsa_next_free_vgpr 256
		.amdhsa_next_free_sgpr 102
		.amdhsa_accum_offset 256
		.amdhsa_reserve_vcc 1
		.amdhsa_float_round_mode_32 0
		.amdhsa_float_round_mode_16_64 0
		.amdhsa_float_denorm_mode_32 3
		.amdhsa_float_denorm_mode_16_64 3
		.amdhsa_dx10_clamp 1
		.amdhsa_ieee_mode 1
		.amdhsa_fp16_overflow 0
		.amdhsa_tg_split 0
		.amdhsa_exception_fp_ieee_invalid_op 0
		.amdhsa_exception_fp_denorm_src 0
		.amdhsa_exception_fp_ieee_div_zero 0
		.amdhsa_exception_fp_ieee_overflow 0
		.amdhsa_exception_fp_ieee_underflow 0
		.amdhsa_exception_fp_ieee_inexact 0
		.amdhsa_exception_int_div_zero 0
	.end_amdhsa_kernel

; __global__ void __launch_bounds__(512, 2) mk_fwd(Args a) {
amdhsa.kernels:
  - .agpr_count:     0
    .args:
      - .offset:         0
        .size:           176
        .value_kind:     by_value
      - .offset:         176
        .size:           4
        .value_kind:     hidden_block_count_x
      - .offset:         180
        .size:           4
        .value_kind:     hidden_block_count_y
      - .offset:         184
        .size:           4
        .value_kind:     hidden_block_count_z
      - .offset:         188
        .size:           2
        .value_kind:     hidden_group_size_x
      - .offset:         190
        .size:           2
        .value_kind:     hidden_group_size_y
      - .offset:         192
        .size:           2
        .value_kind:     hidden_group_size_z
      - .offset:         194
        .size:           2
        .value_kind:     hidden_remainder_x
      - .offset:         196
        .size:           2
        .value_kind:     hidden_remainder_y
      - .offset:         198
        .size:           2
        .value_kind:     hidden_remainder_z
      - .offset:         216
        .size:           8
        .value_kind:     hidden_global_offset_x
      - .offset:         224
        .size:           8
        .value_kind:     hidden_global_offset_y
      - .offset:         232
        .size:           8
        .value_kind:     hidden_global_offset_z
      - .offset:         240
        .size:           2
        .value_kind:     hidden_grid_dims
      - .offset:         264
        .size:           8
        .value_kind:     hidden_multigrid_sync_arg
      - .offset:         296
        .size:           4
        .value_kind:     hidden_dynamic_lds_size
    .group_segment_fixed_size: 0
    .kernarg_segment_align: 8
    .kernarg_segment_size: 432
    .language:       OpenCL C
    .language_version:
      - 2
      - 0
    .max_flat_workgroup_size: 512
    .name:           _Z6mk_fwd4Args
    .private_segment_fixed_size: 0
    .sgpr_count:     108
    .sgpr_spill_count: 163
    .symbol:         _Z6mk_fwd4Args.kd
    .uniform_work_group_size: 1
    .uses_dynamic_stack: false
    .vgpr_count:     256
    .vgpr_spill_count: 0
    .wavefront_size: 64
